# phase 6: loop-invariant gain vectors hoisted out of the row loop; attention: no LDS wait before next-tile prefetch
# speedup vs baseline: 1.0370x; 1.0134x over previous
;     ...
;         const bool more = (i + 1 < nt);
;         if (more) { jn = next(j); if (probe != 1) kv_gload<DV, HAS_V>(st, Kb, VTb, ldv, jn * 64); }
;         if (probe != 2) body(j, (const unsigned char*)(lds + (i & 1) * SB));
;         if (more && probe != 1) kv_sstore<DV, HAS_V>(st, lds + ((i + 1) & 1) * SB);
.Ldl_stage:
	s_add_i32 s65, s24, 2
	s_cmp_ge_u32 s65, s58
	s_cbranch_scc1 .Ldl_next
	s_waitcnt vmcnt(0)

; template <int DV, bool HAS_V>
; DI void kv_sstore(const KVStage<DV>& st, unsigned char* buf) {
;     const int tid = threadIdx.x;
;     *(u32x4*)(buf + (tid >> 3) * KP + (tid & 7) * 16) = st.k[0];
;     if (HAS_V) {
; #pragma unroll
;         for (int i = 0; i < DV / 64; ++i) {
;             const int c = tid + 512 * i, kc = c & 7; unsigned char* q = buf + KT_BYTES + (c >> 3) * VP + (kc >> 1) * 32 + (kc & 1) * 8;
;             u32x2 lo, hi; lo.x = st.v[i].x; lo.y = st.v[i].y; hi.x = st.v[i].z; hi.y = st.v[i].w;
;             *(u32x2*)q = lo; *(u32x2*)(q + 16) = hi;
;         }
;     }
; }
	v_add3_u32 v2, s63, v159, v195
	ds_write_b128 v2, v[146:149]
	v_add3_u32 v2, s63, v196, v197
	v_add_u32_e32 v7, v2, v159
	v_add_u32_e32 v2, v2, v180
	v_add_u32_e32 v7, 0x2000, v7
	v_add_u32_e32 v2, 0x2000, v2
	ds_write2_b64 v7, v[150:151], v[152:153] offset0:128 offset1:130
	ds_write2_b64 v2, v[154:155], v[156:157] offset0:128 offset1:130

;     ...
;         const bool more = (i + 1 < nt);
;         if (more) { jn = next(j); if (probe != 1) kv_gload<DV, HAS_V>(st, Kb, VTb, ldv, jn * 64); }
	s_add_i32 s65, s24, 3
	s_cmp_ge_u32 s65, s58
	s_cbranch_scc1 .Ldl_next

; template <int DV, bool HAS_V>
; DI void kv_gload(KVStage<DV>& st, const bf16_t* __restrict__ Kb, const bf16_t* __restrict__ VTb, int ldv, int key0) {
;     const int tid = threadIdx.x;
;     st.k[0] = *(const u32x4*)(Kb + (size_t)(key0 + (tid >> 3)) * 64 + (tid & 7) * 8);
;     if (HAS_V) {
; #pragma unroll
;         for (int i = 0; i < DV / 64; ++i) { const int c = tid + 512 * i; st.v[i] = *(const u32x4*)(VTb + (size_t)(key0 >> 6) * (DV * 64) + c * 8); }
;     }
; }
	s_lshl_b32 s66, s65, 6
	v_add_u32_e32 v8, s66, v187
	v_mov_b32_e32 v9, v3
	v_lshlrev_b64 v[8:9], 7, v[8:9]
	v_lshl_add_u64 v[8:9], v[4:5], 0, v[8:9]
	global_load_dwordx4 v[146:149], v[8:9], off
	s_lshl_b32 s66, s65, 14
	s_mov_b32 s67, 0
	v_lshl_add_u64 v[10:11], v[164:165], 0, s[66:67]
	global_load_dwordx4 v[150:153], v[10:11], off
	s_add_u32 s66, s66, 0x2000
	v_lshl_add_u64 v[10:11], v[164:165], 0, s[66:67]
	global_load_dwordx4 v[154:157], v[10:11], off


;     ...
;         const bool more = (i + 1 < nt);
;         if (more) { jn = next(j); if (probe != 1) kv_gload<DV, HAS_V>(st, Kb, VTb, ldv, jn * 64); }
;         if (probe != 2) body(j, (const unsigned char*)(lds + (i & 1) * SB));
;         if (more && probe != 1) kv_sstore<DV, HAS_V>(st, lds + ((i + 1) & 1) * SB);
.Lns_stage:
	s_mov_b32 s27, s10
	s_add_i32 s26, s13, 2
	s_cmp_ge_u32 s26, s2
	s_cbranch_scc1 .Lns_next
	s_waitcnt vmcnt(0)

; template <int DV, bool HAS_V>
; DI void kv_sstore(const KVStage<DV>& st, unsigned char* buf) {
;     const int tid = threadIdx.x;
;     *(u32x4*)(buf + (tid >> 3) * KP + (tid & 7) * 16) = st.k[0];
;     if (HAS_V) {
; #pragma unroll
;         for (int i = 0; i < DV / 64; ++i) {
;             const int c = tid + 512 * i, kc = c & 7; unsigned char* q = buf + KT_BYTES + (c >> 3) * VP + (kc >> 1) * 32 + (kc & 1) * 8;
;             u32x2 lo, hi; lo.x = st.v[i].x; lo.y = st.v[i].y; hi.x = st.v[i].z; hi.y = st.v[i].w;
;             *(u32x2*)q = lo; *(u32x2*)(q + 16) = hi;
;         }
;     }
; }
	v_add_u32_e32 v236, s20, v194
	v_add_u32_e32 v237, v236, v195
	v_add3_u32 v236, v236, v196, v197
	v_add_u32_e32 v236, 0x2000, v236
	ds_write_b128 v237, v[114:117]
	ds_write2_b64 v236, v[118:119], v[120:121] offset0:128 offset1:130

;     ...
;         const bool more = (i + 1 < nt);
;         if (more) { jn = next(j); if (probe != 1) kv_gload<DV, HAS_V>(st, Kb, VTb, ldv, jn * 64); }
	s_add_i32 s26, s13, 3
	s_cmp_ge_u32 s26, s2
	s_cbranch_scc1 .Lns_next

; template <int DV, bool HAS_V>
; DI void kv_gload(KVStage<DV>& st, const bf16_t* __restrict__ Kb, const bf16_t* __restrict__ VTb, int ldv, int key0) {
;     const int tid = threadIdx.x;
;     st.k[0] = *(const u32x4*)(Kb + (size_t)(key0 + (tid >> 3)) * 64 + (tid & 7) * 8);
;     if (HAS_V) {
; #pragma unroll
;         for (int i = 0; i < DV / 64; ++i) { const int c = tid + 512 * i; st.v[i] = *(const u32x4*)(VTb + (size_t)(key0 >> 6) * (DV * 64) + c * 8); }
;     }
; }
	s_lshl_b32 s24, s10, 6
	v_add_u32_e32 v188, s24, v187
	v_mov_b32_e32 v189, v173
	v_lshlrev_b64 v[188:189], 7, v[188:189]
	v_lshl_add_u64 v[188:189], v[126:127], 0, v[188:189]
	global_load_dwordx4 v[114:117], v[188:189], off
	s_lshl_b32 s24, s10, 13
	s_mov_b32 s25, 0
	v_lshl_add_u64 v[190:191], v[128:129], 0, s[24:25]
	global_load_dwordx4 v[118:121], v[190:191], off

;     ...
;     for (int i = 0; i < nt; ++i) {
;         const int j = jn;
;         const bool more = (i + 1 < nt);
;         if (more) { jn = next(j); if (probe != 1) kv_gload<DV, HAS_V>(st, Kb, VTb, ldv, jn * 64); }
	s_add_i32 s26, s13, 4
	s_cmp_ge_u32 s26, s2
	s_cbranch_scc1 .Lns_next

;     ...
;         kv_loop<64, true>(lds, Ks, VsT, 4096, nts, j0, [U](int j) { return __ffsll((long long)(U & (~0ull << (j + 1)))) - 1; }, [&](int j, const unsigned char* sb) {
	s_add_i32 s22, s10, 1
	s_lshl_b64 s[22:23], -1, s22
	s_and_b64 s[22:23], s[22:23], s[6:7]
	s_ff1_i32_b64 s27, s[22:23]


; DI float bflo(unsigned u) { return __uint_as_float(u << 16); }
; DI float bfhi(unsigned u) { return __uint_as_float(u & 0xffff0000u); }
; DI void phase6(const Params& p) {
;     const int lane = VTID & 63, w = VTID >> 6;
;     const float* x = p.in[0]; const float* gpost = p.in[15]; const float* gffn = p.in[16];
;     const bf16_t* MIX = (const bf16_t*)(p.ws + OFF_MIX);
;     bf16_t* H = (bf16_t*)(p.ws + OFF_H);
;     float* RSTD = (float*)(p.ws + OFF_GATES);
;     for (int row = VBLK * 4 + w; row < T; row += VGRID * 4) {
;         f32x4 mv[4], xv[4]; float ss = 0.f;
; #pragma unroll
;         for (int i = 0; i < 4; ++i) {
;             const u32x2 u = *(const u32x2*)(MIX + (size_t)row * 1024 + i * 256 + lane * 4);
;             mv[i][0] = bflo(u.x); mv[i][1] = bfhi(u.x); mv[i][2] = bflo(u.y); mv[i][3] = bfhi(u.y);
;             xv[i] = *(const f32x4*)(x + (size_t)row * 1024 + i * 256 + lane * 4);
;             ss += mv[i][0] * mv[i][0] + mv[i][1] * mv[i][1] + mv[i][2] * mv[i][2] + mv[i][3] * mv[i][3];
;         }
;         ss = wave_sum(ss);
;         const float rstd = rsqrtf(ss * (1.f / 1024.f) + NORM_EPS);
;         if (lane == 0) RSTD[row] = rstd;
;         float ss2 = 0.f;
; #pragma unroll
;         for (int i = 0; i < 4; ++i) {
;             const f32x4 gg = *(const f32x4*)(gpost + i * 256 + lane * 4);
; #pragma unroll
;             for (int e = 0; e < 4; ++e) { xv[i][e] += mv[i][e] * rstd * gg[e]; ss2 += xv[i][e] * xv[i][e]; }
;         }
;         ss2 = wave_sum(ss2);
;         const float rstd2 = rsqrtf(ss2 * (1.f / 1024.f) + NORM_EPS);
; #pragma unroll
;         for (int i = 0; i < 4; ++i) {
;             const f32x4 gg = *(const f32x4*)(gffn + i * 256 + lane * 4);
.LBB0_702:
	s_cmp_gt_i32 s90, 6
	s_cselect_b64 s[0:1], -1, 0
	s_cmp_lt_i32 s91, 7
	s_cselect_b64 s[2:3], -1, 0
	s_or_b64 s[0:1], s[0:1], s[2:3]
	v_bfe_u32 v1, v0, 6, 4
	s_and_b64 vcc, exec, s[0:1]
	v_and_b32_e32 v150, 4, v1
	s_cbranch_vccnz .LBB0_758
	v_and_b32_e32 v56, 0x3ff, v0
	v_readlane_b32 s0, v238, 0
	v_bfe_u32 v1, v56, 6, 2
	s_lshl_b32 s0, s0, 3
	v_or3_b32 v18, v150, s0, v1
	s_mov_b32 s0, 0x8000
	v_cmp_gt_i32_e32 vcc, s0, v18
	s_and_saveexec_b64 s[2:3], vcc
	s_cbranch_execz .LBB0_708
	v_mbcnt_lo_u32_b32 v2, -1, 0
	v_mbcnt_hi_u32_b32 v2, -1, v2
	v_and_b32_e32 v4, 64, v2
	v_xor_b32_e32 v3, 32, v2
	v_add_u32_e32 v4, 64, v4
	v_cmp_lt_i32_e32 vcc, v3, v4
	v_readlane_b32 s4, v238, 31
	v_readlane_b32 s5, v238, 32
	v_cndmask_b32_e32 v3, v2, v3, vcc
	v_lshlrev_b32_e32 v57, 2, v3
	v_xor_b32_e32 v3, 16, v2
	v_cmp_lt_i32_e32 vcc, v3, v4
	v_readlane_b32 s6, v238, 33
	v_readlane_b32 s7, v238, 34
	v_cndmask_b32_e32 v3, v2, v3, vcc
	v_lshlrev_b32_e32 v58, 2, v3
	v_xor_b32_e32 v3, 8, v2
	v_cmp_lt_i32_e32 vcc, v3, v4
	v_readlane_b32 s8, v238, 35
	v_readlane_b32 s9, v238, 36
	v_cndmask_b32_e32 v3, v2, v3, vcc
	v_lshlrev_b32_e32 v59, 2, v3
	v_xor_b32_e32 v3, 4, v2
	v_cmp_lt_i32_e32 vcc, v3, v4
	v_readlane_b32 s10, v238, 37
	v_readlane_b32 s11, v238, 38
	v_cndmask_b32_e32 v3, v2, v3, vcc
	v_lshlrev_b32_e32 v60, 2, v3
	v_xor_b32_e32 v3, 2, v2
	v_cmp_lt_i32_e32 vcc, v3, v4
	v_and_b32_e32 v1, 63, v56
	v_readlane_b32 s4, v238, 1
	v_cndmask_b32_e32 v3, v2, v3, vcc
	v_lshlrev_b32_e32 v61, 2, v3
	v_xor_b32_e32 v3, 1, v2
	v_cmp_lt_i32_e32 vcc, v3, v4
	v_readlane_b32 s12, v238, 39
	v_readlane_b32 s13, v238, 40
	v_cndmask_b32_e32 v2, v2, v3, vcc
	v_lshlrev_b32_e32 v62, 2, v2
	v_lshlrev_b32_e32 v2, 4, v1
	v_mov_b32_e32 v3, 0
	v_readlane_b32 s14, v238, 41
	v_readlane_b32 s15, v238, 42
	v_readlane_b32 s16, v238, 43
	v_readlane_b32 s17, v238, 44
	v_readlane_b32 s18, v238, 45
	v_readlane_b32 s19, v238, 46
	v_readlane_b32 s5, v238, 2
	v_ashrrev_i32_e32 v19, 31, v18
	v_mov_b64_e32 v[4:5], 0x18ba5800
	v_lshl_add_u64 v[20:21], s[18:19], 0, v[2:3]
	v_readlane_b32 s6, v238, 3
	v_lshl_add_u64 v[22:23], s[4:5], 0, v[2:3]
	v_readlane_b32 s4, v238, 10
	v_lshl_add_u64 v[24:25], v[18:19], 2, v[4:5]
	v_lshlrev_b64 v[4:5], 12, v[18:19]
	v_readlane_b32 s12, v238, 15
	v_readlane_b32 s7, v238, 4
	v_readlane_b32 s5, v238, 11
	s_lshl_b32 s6, s4, 3
	v_or_b32_e32 v4, v4, v2
	v_readlane_b32 s13, v238, 16
	v_readlane_b32 s8, v238, 5
	v_readlane_b32 s9, v238, 6
	v_readlane_b32 s10, v238, 7
	v_readlane_b32 s11, v238, 8
	s_ashr_i32 s7, s6, 31
	v_lshlrev_b64 v[26:27], 11, v[18:19]
	v_readlane_b32 s14, v238, 17
	v_readlane_b32 s15, v238, 18
	v_readlane_b32 s16, v238, 19
	v_readlane_b32 s17, v238, 20
	v_lshl_add_u64 v[2:3], s[12:13], 0, v[4:5]
	s_mov_b64 s[4:5], 0xc00
	v_cmp_eq_u32_e64 s[0:1], 0, v1
	s_lshl_b64 s[8:9], s[6:7], 2
	v_lshl_or_b32 v26, v1, 3, v26
	s_lshl_b64 s[10:11], s[6:7], 11
	v_lshl_add_u64 v[28:29], v[2:3], 0, s[4:5]
	s_lshl_b64 s[12:13], s[6:7], 12
	s_mov_b64 s[14:15], 0
	v_mov_b32_e32 v63, 0x358637bd
	s_mov_b32 s7, 0x800000
	s_mov_b32 s16, 0x1ba5000
	s_movk_i32 s17, 0x7fff
	v_readlane_b32 s18, v238, 21
	v_readlane_b32 s19, v238, 22
	v_readlane_b32 s20, v238, 23
	v_readlane_b32 s21, v238, 24
	v_readlane_b32 s22, v238, 25
	v_readlane_b32 s23, v238, 26
	v_readlane_b32 s24, v238, 27
	v_readlane_b32 s25, v238, 28
	v_readlane_b32 s26, v238, 29
	v_readlane_b32 s27, v238, 30
	global_load_dwordx4 v[200:203], v[20:21], off
	global_load_dwordx4 v[204:207], v[20:21], off offset:1024
	global_load_dwordx4 v[208:211], v[20:21], off offset:2048
	global_load_dwordx4 v[212:215], v[20:21], off offset:3072
	global_load_dwordx4 v[216:219], v[22:23], off
	global_load_dwordx4 v[220:223], v[22:23], off offset:1024
	global_load_dwordx4 v[224:227], v[22:23], off offset:2048
	global_load_dwordx4 v[228:231], v[22:23], off offset:3072
	s_waitcnt vmcnt(0)

; DI unsigned pk_bf16(float a, float b) { f32x2 v = {a, b}; return __builtin_bit_cast(unsigned, __builtin_convertvector(v, bf16v2)); }
; DI float bflo(unsigned u) { return __uint_as_float(u << 16); }
; DI float bfhi(unsigned u) { return __uint_as_float(u & 0xffff0000u); }
; DI void phase6(const Params& p) {
;     ...
;         f32x4 mv[4], xv[4]; float ss = 0.f;
; #pragma unroll
;         for (int i = 0; i < 4; ++i) {
;             const u32x2 u = *(const u32x2*)(MIX + (size_t)row * 1024 + i * 256 + lane * 4);
;             mv[i][0] = bflo(u.x); mv[i][1] = bfhi(u.x); mv[i][2] = bflo(u.y); mv[i][3] = bfhi(u.y);
;             xv[i] = *(const f32x4*)(x + (size_t)row * 1024 + i * 256 + lane * 4);
;             ss += mv[i][0] * mv[i][0] + mv[i][1] * mv[i][1] + mv[i][2] * mv[i][2] + mv[i][3] * mv[i][3];
;         }
;         ss = wave_sum(ss);
;         const float rstd = rsqrtf(ss * (1.f / 1024.f) + NORM_EPS);
;         if (lane == 0) RSTD[row] = rstd;
;         float ss2 = 0.f;
; #pragma unroll
;         for (int i = 0; i < 4; ++i) {
;             const f32x4 gg = *(const f32x4*)(gpost + i * 256 + lane * 4);
; #pragma unroll
;             for (int e = 0; e < 4; ++e) { xv[i][e] += mv[i][e] * rstd * gg[e]; ss2 += xv[i][e] * xv[i][e]; }
;         }
;         ss2 = wave_sum(ss2);
;         const float rstd2 = rsqrtf(ss2 * (1.f / 1024.f) + NORM_EPS);
; #pragma unroll
;         for (int i = 0; i < 4; ++i) {
;             const f32x4 gg = *(const f32x4*)(gffn + i * 256 + lane * 4);
;             u32x2 o; o.x = pk_bf16(xv[i][0] * rstd2 * gg[0], xv[i][1] * rstd2 * gg[1]); o.y = pk_bf16(xv[i][2] * rstd2 * gg[2], xv[i][3] * rstd2 * gg[3]);
;             *(u32x2*)(H + (size_t)row * 1024 + i * 256 + lane * 4) = o;
;         }
	s_branch .LBB0_706
.LBB0_705:
	s_or_b64 exec, exec, s[4:5]
	v_mov_b32_e32 v39, v51
	v_mov_b32_e32 v41, v45
	v_mov_b32_e32 v45, v53
	v_mov_b32_e32 v33, v1
	v_mov_b32_e32 v35, v19
	v_mov_b32_e32 v43, v47
	v_pk_mul_f32 v[32:33], v[48:49], v[32:33] op_sel_hi:[0,1]
	v_pk_mul_f32 v[34:35], v[48:49], v[34:35] op_sel_hi:[0,1]
	v_pk_mul_f32 v[42:43], v[48:49], v[42:43] op_sel_hi:[0,1]
	v_mov_b32_e32 v37, v49
	v_pk_mul_f32 v[40:41], v[48:49], v[40:41] op_sel_hi:[0,1]
	v_pk_mul_f32 v[36:37], v[48:49], v[36:37] op_sel_hi:[0,1]
	v_pk_mul_f32 v[38:39], v[48:49], v[38:39] op_sel_hi:[0,1]
	v_mov_b32_e32 v47, v55
	v_pk_mul_f32 v[44:45], v[48:49], v[44:45] op_sel_hi:[0,1]
	v_pk_mul_f32 v[46:47], v[48:49], v[46:47] op_sel_hi:[0,1]
	v_add_co_u32_e64 v30, s[4:5], s16, v30
	v_add_u32_e32 v18, s6, v18
	s_nop 0
	v_addc_co_u32_e64 v31, s[4:5], 0, v31, s[4:5]
	v_lshl_add_u64 v[24:25], v[24:25], 0, s[8:9]
	v_lshl_add_u64 v[26:27], v[26:27], 0, s[10:11]
	v_lshl_add_u64 v[28:29], v[28:29], 0, s[12:13]
	s_waitcnt vmcnt(0)
	v_pk_fma_f32 v[14:15], v[32:33], v[200:201], v[14:15]
	v_pk_fma_f32 v[16:17], v[34:35], v[202:203], v[16:17]
	s_waitcnt vmcnt(2)
	v_pk_fma_f32 v[32:33], v[42:43], v[210:211], v[4:5]
	v_pk_mul_f32 v[4:5], v[14:15], v[14:15]
	v_pk_fma_f32 v[34:35], v[40:41], v[208:209], v[2:3]
	v_pk_mul_f32 v[2:3], v[16:17], v[16:17]
	v_add_f32_e32 v1, v4, v5
	v_pk_fma_f32 v[10:11], v[36:37], v[204:205], v[10:11]
	v_add_f32_e32 v1, v2, v1
	v_pk_fma_f32 v[12:13], v[38:39], v[206:207], v[12:13]
	v_pk_mul_f32 v[38:39], v[10:11], v[10:11]
	v_add_f32_e32 v1, v3, v1
	v_add_f32_e32 v1, v38, v1
	v_pk_mul_f32 v[36:37], v[12:13], v[12:13]
	v_add_f32_e32 v1, v39, v1
	v_add_f32_e32 v1, v36, v1
	v_pk_mul_f32 v[42:43], v[34:35], v[34:35]
	v_add_f32_e32 v1, v37, v1
	v_add_f32_e32 v1, v42, v1
	v_pk_mul_f32 v[40:41], v[32:33], v[32:33]
	v_add_f32_e32 v1, v43, v1
	s_waitcnt vmcnt(1)
	v_pk_fma_f32 v[6:7], v[44:45], v[212:213], v[6:7]
	v_add_f32_e32 v1, v40, v1
	v_pk_fma_f32 v[8:9], v[46:47], v[214:215], v[8:9]
	v_pk_mul_f32 v[46:47], v[6:7], v[6:7]
	v_add_f32_e32 v1, v41, v1
	v_add_f32_e32 v1, v46, v1
	v_pk_mul_f32 v[44:45], v[8:9], v[8:9]
	v_add_f32_e32 v1, v47, v1
	v_add_f32_e32 v1, v44, v1
	v_add_f32_e32 v1, v45, v1
	ds_bpermute_b32 v2, v57, v1
	s_waitcnt lgkmcnt(0)
	v_add_f32_e32 v1, v1, v2
	ds_bpermute_b32 v2, v58, v1
	s_waitcnt lgkmcnt(0)
	v_add_f32_e32 v1, v1, v2
	ds_bpermute_b32 v2, v59, v1
	s_waitcnt lgkmcnt(0)
	v_add_f32_e32 v1, v1, v2
	ds_bpermute_b32 v2, v60, v1
	s_waitcnt lgkmcnt(0)
	v_add_f32_e32 v1, v1, v2
	ds_bpermute_b32 v2, v61, v1
	s_waitcnt lgkmcnt(0)
	v_add_f32_e32 v1, v1, v2
	ds_bpermute_b32 v2, v62, v1
	s_waitcnt lgkmcnt(0)
	v_add_f32_e32 v1, v1, v2
	v_fmamk_f32 v1, v1, 0x3a800000, v63
	v_mul_f32_e32 v2, 0x4b800000, v1
	v_cmp_gt_f32_e32 vcc, s7, v1
	s_nop 1
	v_cndmask_b32_e32 v1, v1, v2, vcc
	v_rsq_f32_e32 v1, v1
	s_nop 0
	v_mul_f32_e32 v2, 0x45800000, v1
	v_cndmask_b32_e32 v36, v1, v2, vcc
	v_pk_mul_f32 v[2:3], v[14:15], v[36:37] op_sel_hi:[1,0]
	v_pk_mul_f32 v[4:5], v[16:17], v[36:37] op_sel_hi:[1,0]
	s_waitcnt vmcnt(0)
	v_pk_mul_f32 v[2:3], v[216:217], v[2:3]
	v_pk_mul_f32 v[4:5], v[218:219], v[4:5]
	v_cvt_pk_bf16_f32 v2, v2, v3
	v_cvt_pk_bf16_f32 v3, v4, v5
	global_store_dwordx2 v[30:31], v[2:3], off offset:2048
	v_pk_mul_f32 v[10:11], v[10:11], v[36:37] op_sel_hi:[1,0]
	v_pk_mul_f32 v[12:13], v[12:13], v[36:37] op_sel_hi:[1,0]
	v_pk_mul_f32 v[6:7], v[6:7], v[36:37] op_sel_hi:[1,0]
	v_pk_mul_f32 v[8:9], v[8:9], v[36:37] op_sel_hi:[1,0]
	v_cmp_lt_i32_e32 vcc, s17, v18
	s_or_b64 s[14:15], vcc, s[14:15]
	v_pk_mul_f32 v[2:3], v[220:221], v[10:11]
	v_pk_mul_f32 v[4:5], v[222:223], v[12:13]
	v_cvt_pk_bf16_f32 v2, v2, v3
	v_cvt_pk_bf16_f32 v3, v4, v5
	global_store_dwordx2 v[30:31], v[2:3], off offset:2560
	v_pk_mul_f32 v[10:11], v[34:35], v[36:37] op_sel_hi:[1,0]
	v_pk_mul_f32 v[12:13], v[32:33], v[36:37] op_sel_hi:[1,0]
	v_pk_mul_f32 v[2:3], v[224:225], v[10:11]
	v_pk_mul_f32 v[4:5], v[226:227], v[12:13]
	v_cvt_pk_bf16_f32 v2, v2, v3
	v_cvt_pk_bf16_f32 v3, v4, v5
	global_store_dwordx2 v[30:31], v[2:3], off offset:3072
	s_nop 1
	v_pk_mul_f32 v[2:3], v[228:229], v[6:7]
	v_pk_mul_f32 v[4:5], v[230:231], v[8:9]
	v_cvt_pk_bf16_f32 v2, v2, v3
	v_cvt_pk_bf16_f32 v3, v4, v5
	global_store_dwordx2 v[30:31], v[2:3], off offset:3584
	s_andn2_b64 exec, exec, s[14:15]
	s_cbranch_execz .LBB0_708
